# MLA: next-tile LDS writes and global prefetch woven between the QK MFMAs
# speedup vs baseline: 1.1263x; 1.0023x over previous
; DI f4 mfma16(h8 a, h8 b, f4 c) { return __builtin_amdgcn_mfma_f32_16x16x32_f16(a, b, c, 0, 0, 0); }
; template <int DQK, bool BIAS>
; __device__ __forceinline__ void attn_pass(const hf* __restrict__ Q, int ldq, const hf* __restrict__ Kp, int ldk, const hf* __restrict__ VT,
;                                           int s0, int L, int q0, float scale_l2, const float* sBias, f4 (&oacc)[8][4], char* smem) {
;     ...
;   auto loadKV = [&](int kt) {
;     const int key0 = kt * 64;
; #pragma unroll
;     for (int i = 0; i < NKL; ++i) rk[i] = *(const u4*)(Kp + (size_t)(s0 + key0 + (tid >> 2)) * ldk + ((tid & 3) + 4 * i) * 8);
; #pragma unroll
;     for (int i = 0; i < 4; ++i) { int idx = tid + 256 * i, dv = idx >> 3, ch = idx & 7; rv[i] = *(const u4*)(VT + (size_t)dv * T_TOK + s0 + key0 + ch * 8); }
;   };
;   auto storeKV = [&](int st) {
;     hf* sK = sbase + st * A_STG; hf* sVT = sK + 64 * 104;
; #pragma unroll
;     for (int i = 0; i < NKL; ++i) *(u4*)(sK + (tid >> 2) * KS + (((tid & 3) ^ (((tid >> 4) ^ (tid >> 5)) & 1)) + 4 * i) * 8) = rk[i];
; #pragma unroll
;     for (int i = 0; i < 4; ++i) { int idx = tid + 256 * i, dv = idx >> 3, ch = idx & 7; *(u4*)(sVT + dv * 72 + ch * 8) = rv[i]; }
;     ...
;     for (int mk = 0; mk < 4; ++mk) {
;       h8 kf[NKS];
; #pragma unroll
;       for (int ks = 0; ks < NKS; ++ks) kf[ks] = *(const h8*)(sK + (mk * 16 + fr) * KS + ks * 32 + (fq ^ (((fr >> 2) ^ (fr >> 3)) & 1)) * 8);
; #pragma unroll
;       for (int nq = 0; nq < 4; ++nq) {
;         f4 a = {0.f, 0.f, 0.f, 0.f};
; #pragma unroll
;         for (int ks = 0; ks < NKS; ++ks) a = mfma16(kf[ks], qf[nq][ks], a);
;         sacc[mk][nq] = a;
;       }
;     }
;     if (kt + 1 < nkt) storeKV((kt + 1) & 1);
;     if (kt + 2 < nkt) loadKV(kt + 2);
.LBB0_1994:
	s_bitcmp1_b32 s19, 0
	s_cselect_b32 s14, 0x7c00, 0
	s_add_i32 s15, s14, 16
	v_add3_u32 v64, s15, v208, v233
	ds_read_b128 v[48:51], v64
	ds_read_b128 v[52:55], v64 offset:64
	ds_read_b128 v[56:59], v64 offset:128
	ds_read_b128 v[60:63], v64 offset:3328
	ds_read_b128 v[88:91], v64 offset:3392
	ds_read_b128 v[92:95], v64 offset:3456
	ds_read_b128 v[96:99], v64 offset:6656
	ds_read_b128 v[100:103], v64 offset:6720
	ds_read_b128 v[108:111], v64 offset:6784
	ds_read_b128 v[112:115], v64 offset:9984
	ds_read_b128 v[116:119], v64 offset:10048
	ds_read_b128 v[120:123], v64 offset:10112
	s_add_i32 s14, s19, 1
	s_waitcnt lgkmcnt(11)
	v_mfma_f32_16x16x32_f16 v[68:71], v[48:51], v[0:3], 0
	s_waitcnt lgkmcnt(10)
	v_mfma_f32_16x16x32_f16 v[68:71], v[52:55], v[4:7], v[68:71]
	s_waitcnt lgkmcnt(9)
	v_mfma_f32_16x16x32_f16 v[68:71], v[56:59], v[8:11], v[68:71]
	v_mfma_f32_16x16x32_f16 v[172:175], v[48:51], v[24:27], 0
	v_mfma_f32_16x16x32_f16 v[172:175], v[52:55], v[28:31], v[172:175]
	v_mfma_f32_16x16x32_f16 v[80:83], v[48:51], v[12:15], 0
	v_mfma_f32_16x16x32_f16 v[172:175], v[56:59], v[32:35], v[172:175]
	v_mfma_f32_16x16x32_f16 v[124:127], v[48:51], v[36:39], 0
	v_mfma_f32_16x16x32_f16 v[80:83], v[52:55], v[16:19], v[80:83]
	v_mfma_f32_16x16x32_f16 v[124:127], v[52:55], v[40:43], v[124:127]
	v_mfma_f32_16x16x32_f16 v[80:83], v[56:59], v[20:23], v[80:83]
	s_waitcnt lgkmcnt(8)
	v_mfma_f32_16x16x32_f16 v[204:207], v[60:63], v[0:3], 0
	s_cmp_ge_u32 s14, s18
	s_cbranch_scc1 .Lqm_noW
	s_waitcnt lgkmcnt(7)
	v_mfma_f32_16x16x32_f16 v[204:207], v[88:91], v[4:7], v[204:207]
	s_bitcmp1_b32 s14, 0
	s_waitcnt lgkmcnt(6)
	v_mfma_f32_16x16x32_f16 v[204:207], v[92:95], v[8:11], v[204:207]
	s_cselect_b32 s27, 0x7c00, 0
	v_mfma_f32_16x16x32_f16 v[72:75], v[60:63], v[12:15], 0
	s_add_i32 s27, s27, 16
	v_mfma_f32_16x16x32_f16 v[72:75], v[88:91], v[16:19], v[72:75]
	v_add3_u32 v130, s27, v213, v238
	v_mfma_f32_16x16x32_f16 v[72:75], v[92:95], v[20:23], v[72:75]
	s_waitcnt vmcnt(6)
	v_mfma_f32_16x16x32_f16 v[168:171], v[60:63], v[24:27], 0
	ds_write_b128 v130, v[246:249]
	v_mfma_f32_16x16x32_f16 v[168:171], v[88:91], v[28:31], v[168:171]
	s_waitcnt vmcnt(1)
	v_mfma_f32_16x16x32_f16 v[168:171], v[92:95], v[32:35], v[168:171]
	ds_write_b128 v130, a[196:199] offset:64
	v_mfma_f32_16x16x32_f16 v[104:107], v[60:63], v[36:39], 0
	s_waitcnt vmcnt(0)
	v_mfma_f32_16x16x32_f16 v[104:107], v[88:91], v[40:43], v[104:107]
	ds_write_b128 v130, a[204:207] offset:128
	v_mfma_f32_16x16x32_f16 v[104:107], v[92:95], v[44:47], v[104:107]
	v_add3_u32 v130, s27, v229, v212
	s_waitcnt lgkmcnt(5)
	v_mfma_f32_16x16x32_f16 v[200:203], v[96:99], v[0:3], 0
	ds_write_b128 v130, v[250:253] offset:13312
	v_mfma_f32_16x16x32_f16 v[124:127], v[56:59], v[44:47], v[124:127]
	v_add3_u32 v130, s27, v230, v212
	s_waitcnt lgkmcnt(4)
	v_mfma_f32_16x16x32_f16 v[200:203], v[100:103], v[4:7], v[200:203]
	ds_write_b128 v130, a[192:195] offset:13312
	s_waitcnt lgkmcnt(3)
	v_mfma_f32_16x16x32_f16 v[200:203], v[108:111], v[8:11], v[200:203]
	v_add3_u32 v130, s27, v231, v212
	v_mfma_f32_16x16x32_f16 v[188:191], v[96:99], v[12:15], 0
	ds_write_b128 v130, a[200:203] offset:13312
	v_mfma_f32_16x16x32_f16 v[188:191], v[100:103], v[16:19], v[188:191]
	v_add3_u32 v130, s27, v232, v212
	v_mfma_f32_16x16x32_f16 v[188:191], v[108:111], v[20:23], v[188:191]
	ds_write_b128 v130, a[208:211] offset:13312
	s_branch .Lqm_joinW
; DI f4 mfma16(h8 a, h8 b, f4 c) { return __builtin_amdgcn_mfma_f32_16x16x32_f16(a, b, c, 0, 0, 0); }
; template <int DQK, bool BIAS>
; __device__ __forceinline__ void attn_pass(const hf* __restrict__ Q, int ldq, const hf* __restrict__ Kp, int ldk, const hf* __restrict__ VT,
;                                           int s0, int L, int q0, float scale_l2, const float* sBias, f4 (&oacc)[8][4], char* smem) {
;     ...
;   auto loadKV = [&](int kt) {
;     const int key0 = kt * 64;
; #pragma unroll
;     for (int i = 0; i < NKL; ++i) rk[i] = *(const u4*)(Kp + (size_t)(s0 + key0 + (tid >> 2)) * ldk + ((tid & 3) + 4 * i) * 8);
; #pragma unroll
;     for (int i = 0; i < 4; ++i) { int idx = tid + 256 * i, dv = idx >> 3, ch = idx & 7; rv[i] = *(const u4*)(VT + (size_t)dv * T_TOK + s0 + key0 + ch * 8); }
;   };
;   auto storeKV = [&](int st) {
;     hf* sK = sbase + st * A_STG; hf* sVT = sK + 64 * 104;
; #pragma unroll
;     for (int i = 0; i < NKL; ++i) *(u4*)(sK + (tid >> 2) * KS + (((tid & 3) ^ (((tid >> 4) ^ (tid >> 5)) & 1)) + 4 * i) * 8) = rk[i];
; #pragma unroll
;     for (int i = 0; i < 4; ++i) { int idx = tid + 256 * i, dv = idx >> 3, ch = idx & 7; *(u4*)(sVT + dv * 72 + ch * 8) = rv[i]; }
;     ...
;     for (int mk = 0; mk < 4; ++mk) {
;       h8 kf[NKS];
; #pragma unroll
;       for (int ks = 0; ks < NKS; ++ks) kf[ks] = *(const h8*)(sK + (mk * 16 + fr) * KS + ks * 32 + (fq ^ (((fr >> 2) ^ (fr >> 3)) & 1)) * 8);
; #pragma unroll
;       for (int nq = 0; nq < 4; ++nq) {
;         f4 a = {0.f, 0.f, 0.f, 0.f};
; #pragma unroll
;         for (int ks = 0; ks < NKS; ++ks) a = mfma16(kf[ks], qf[nq][ks], a);
;         sacc[mk][nq] = a;
;       }
;     }
;     if (kt + 1 < nkt) storeKV((kt + 1) & 1);
;     if (kt + 2 < nkt) loadKV(kt + 2);
.Lqm_noW:
	s_waitcnt lgkmcnt(7)
	v_mfma_f32_16x16x32_f16 v[204:207], v[88:91], v[4:7], v[204:207]
	s_waitcnt lgkmcnt(6)
	v_mfma_f32_16x16x32_f16 v[204:207], v[92:95], v[8:11], v[204:207]
	v_mfma_f32_16x16x32_f16 v[72:75], v[60:63], v[12:15], 0
	v_mfma_f32_16x16x32_f16 v[72:75], v[88:91], v[16:19], v[72:75]
	v_mfma_f32_16x16x32_f16 v[72:75], v[92:95], v[20:23], v[72:75]
	v_mfma_f32_16x16x32_f16 v[168:171], v[60:63], v[24:27], 0
	v_mfma_f32_16x16x32_f16 v[168:171], v[88:91], v[28:31], v[168:171]
	v_mfma_f32_16x16x32_f16 v[168:171], v[92:95], v[32:35], v[168:171]
	v_mfma_f32_16x16x32_f16 v[104:107], v[60:63], v[36:39], 0
	v_mfma_f32_16x16x32_f16 v[104:107], v[88:91], v[40:43], v[104:107]
	v_mfma_f32_16x16x32_f16 v[104:107], v[92:95], v[44:47], v[104:107]
	s_waitcnt lgkmcnt(5)
	v_mfma_f32_16x16x32_f16 v[200:203], v[96:99], v[0:3], 0
	v_mfma_f32_16x16x32_f16 v[124:127], v[56:59], v[44:47], v[124:127]
	s_waitcnt lgkmcnt(4)
	v_mfma_f32_16x16x32_f16 v[200:203], v[100:103], v[4:7], v[200:203]
	s_waitcnt lgkmcnt(3)
	v_mfma_f32_16x16x32_f16 v[200:203], v[108:111], v[8:11], v[200:203]
	v_mfma_f32_16x16x32_f16 v[188:191], v[96:99], v[12:15], 0
	v_mfma_f32_16x16x32_f16 v[188:191], v[100:103], v[16:19], v[188:191]
	v_mfma_f32_16x16x32_f16 v[188:191], v[108:111], v[20:23], v[188:191]
.Lqm_joinW:
	s_add_i32 s19, s19, 2
	s_cmp_ge_u32 s19, s18
	s_cbranch_scc1 .Lqm_noL
	v_mfma_f32_16x16x32_f16 v[164:167], v[96:99], v[24:27], 0
	v_add_u32_e32 v130, s12, v228
	v_mfma_f32_16x16x32_f16 v[164:167], v[100:103], v[28:31], v[164:167]
	v_mad_i64_i32 v[130:131], s[38:39], v130, s3, v[222:223]
	v_mfma_f32_16x16x32_f16 v[164:167], v[108:111], v[32:35], v[164:167]
	s_lshl_b64 s[38:39], s[12:13], 1
	v_mfma_f32_16x16x32_f16 v[84:87], v[96:99], v[36:39], 0
	global_load_dwordx4 v[246:249], v[130:131], off
	v_mfma_f32_16x16x32_f16 v[84:87], v[100:103], v[40:43], v[84:87]
	global_load_dwordx4 a[196:199], v[130:131], off offset:64
	s_waitcnt lgkmcnt(2)
	v_mfma_f32_16x16x32_f16 v[196:199], v[112:115], v[0:3], 0
	v_lshl_add_u64 v[132:133], v[214:215], 0, s[38:39]
	s_waitcnt lgkmcnt(1)
	v_mfma_f32_16x16x32_f16 v[196:199], v[116:119], v[4:7], v[196:199]
	global_load_dwordx4 a[204:207], v[130:131], off offset:128
	s_waitcnt lgkmcnt(0)
	v_mfma_f32_16x16x32_f16 v[196:199], v[120:123], v[8:11], v[196:199]
	global_load_dwordx4 v[250:253], v[132:133], off
	v_mfma_f32_16x16x32_f16 v[184:187], v[112:115], v[12:15], 0
	v_lshl_add_u64 v[130:131], v[216:217], 0, s[38:39]
	v_mfma_f32_16x16x32_f16 v[184:187], v[116:119], v[16:19], v[184:187]
	v_lshl_add_u64 v[132:133], v[218:219], 0, s[38:39]
	v_mfma_f32_16x16x32_f16 v[184:187], v[120:123], v[20:23], v[184:187]
	global_load_dwordx4 a[192:195], v[130:131], off
	v_mfma_f32_16x16x32_f16 v[160:163], v[112:115], v[24:27], 0
	global_load_dwordx4 a[200:203], v[132:133], off
	v_mfma_f32_16x16x32_f16 v[160:163], v[116:119], v[28:31], v[160:163]
	v_lshl_add_u64 v[130:131], v[220:221], 0, s[38:39]
	v_mfma_f32_16x16x32_f16 v[160:163], v[120:123], v[32:35], v[160:163]
	global_load_dwordx4 a[208:211], v[130:131], off
	v_mfma_f32_16x16x32_f16 v[76:79], v[112:115], v[36:39], 0
	v_mfma_f32_16x16x32_f16 v[76:79], v[116:119], v[40:43], v[76:79]
	v_mfma_f32_16x16x32_f16 v[84:87], v[108:111], v[44:47], v[84:87]
	v_mfma_f32_16x16x32_f16 v[76:79], v[120:123], v[44:47], v[76:79]
	s_branch .LBB0_1998
.Lqm_noL:
	v_mfma_f32_16x16x32_f16 v[164:167], v[96:99], v[24:27], 0
	v_mfma_f32_16x16x32_f16 v[164:167], v[100:103], v[28:31], v[164:167]
	v_mfma_f32_16x16x32_f16 v[164:167], v[108:111], v[32:35], v[164:167]
	v_mfma_f32_16x16x32_f16 v[84:87], v[96:99], v[36:39], 0
	v_mfma_f32_16x16x32_f16 v[84:87], v[100:103], v[40:43], v[84:87]
	s_waitcnt lgkmcnt(2)
	v_mfma_f32_16x16x32_f16 v[196:199], v[112:115], v[0:3], 0
	s_waitcnt lgkmcnt(1)
	v_mfma_f32_16x16x32_f16 v[196:199], v[116:119], v[4:7], v[196:199]
	s_waitcnt lgkmcnt(0)
	v_mfma_f32_16x16x32_f16 v[196:199], v[120:123], v[8:11], v[196:199]
	v_mfma_f32_16x16x32_f16 v[184:187], v[112:115], v[12:15], 0
	v_mfma_f32_16x16x32_f16 v[184:187], v[116:119], v[16:19], v[184:187]
	v_mfma_f32_16x16x32_f16 v[184:187], v[120:123], v[20:23], v[184:187]
	v_mfma_f32_16x16x32_f16 v[160:163], v[112:115], v[24:27], 0
	v_mfma_f32_16x16x32_f16 v[160:163], v[116:119], v[28:31], v[160:163]
	v_mfma_f32_16x16x32_f16 v[160:163], v[120:123], v[32:35], v[160:163]
	v_mfma_f32_16x16x32_f16 v[76:79], v[112:115], v[36:39], 0
	v_mfma_f32_16x16x32_f16 v[76:79], v[116:119], v[40:43], v[76:79]
	v_mfma_f32_16x16x32_f16 v[84:87], v[108:111], v[44:47], v[84:87]
	v_mfma_f32_16x16x32_f16 v[76:79], v[120:123], v[44:47], v[76:79]
